# weight prep moved into the prep phase, run by the 160 workgroups that have no modulation item (overlaps the modulation GEMV; hnorm L0 phase no longer carries it)
# baseline (speedup 1.0000x reference)
.Lwp_entry:
	s_mov_b64 s[84:85], s[0:1]
	s_mov_b32 s86, s18
	s_mov_b32 s87, s19
	s_mov_b64 s[88:89], s[22:23]
	s_mov_b64 s[92:93], s[26:27]
	s_mov_b64 s[94:95], s[30:31]
	v_mov_b32_e32 v120, v0
	v_mov_b32_e32 v121, v1
	v_mov_b32_e32 v122, v57
	s_load_dwordx8 s[52:59], s[0:1], 0x40
	s_waitcnt lgkmcnt(0)
	s_waitcnt vmcnt(0)
	v_and_b32_e32 v105, 15, v143
	v_bfe_u32 v106, v143, 4, 2
	v_lshlrev_b32_e32 v107, 5, v106
	v_mov_b32_e32 v108, 0
	v_mov_b32_e32 v109, 0
	v_mov_b32_e32 v110, 0
	v_mov_b32_e32 v111, 0
	v_readfirstlane_b32 s0, v143
	s_lshr_b32 s0, s0, 6
	v_readlane_b32 s1, v253, 0
	s_sub_u32 s1, s1, 96
	s_lshl_b32 s1, s1, 3
	s_add_i32 s21, s1, s0
	s_movk_i32 s19, 1280
	v_readlane_b32 s4, v253, 15
	v_readlane_b32 s5, v253, 16
	s_add_u32 s6, s50, 0
	s_addc_u32 s7, s51, 0
	s_mov_b32 s8, 10368
	s_mov_b32 s9, 2048
	s_mov_b32 s10, 176
	s_mov_b32 s11, 5632
	s_mov_b32 s12, 0x1745d18
	s_mov_b32 s13, 0
	s_mov_b32 s16, 162
	s_mov_b64 s[14:15], 0
	s_mov_b32 s20, 0
	s_branch .Lwp_mat
.Lwp_ret_0:
	s_mov_b64 s[4:5], s[54:55]
	s_add_u32 s6, s50, 11534336
	s_addc_u32 s7, s51, 0
	s_mov_b32 s8, 2304
	s_mov_b32 s9, 512
	s_mov_b32 s10, 40
	s_mov_b32 s11, 320
	s_mov_b32 s12, 0x6666667
	s_mov_b32 s13, 0
	s_mov_b32 s16, 36
	s_mov_b64 s[14:15], s[52:53]
	s_mov_b32 s20, 1
	s_branch .Lwp_mat
.Lwp_ret_1:
	s_mov_b64 s[4:5], s[58:59]
	s_add_u32 s6, s50, 12189696
	s_addc_u32 s7, s51, 0
	s_mov_b32 s8, 3072
	s_mov_b32 s9, 256
	s_mov_b32 s10, 48
	s_mov_b32 s11, 192
	s_mov_b32 s12, 0x5555556
	s_mov_b32 s13, 0
	s_mov_b32 s16, 48
	s_mov_b64 s[14:15], s[56:57]
	s_mov_b32 s20, 2
	s_branch .Lwp_mat

.Lwp_ret_5:
	s_mov_b64 s[4:5], s[54:55]
	s_add_u32 s4, s4, 589824
	s_addc_u32 s5, s5, 0
	s_add_u32 s6, s50, 11862016
	s_addc_u32 s7, s51, 0
	s_mov_b32 s8, 2304
	s_mov_b32 s9, 512
	s_mov_b32 s10, 40
	s_mov_b32 s11, 320
	s_mov_b32 s12, 0x6666667
	s_mov_b32 s13, 0
	s_mov_b32 s16, 36
	s_mov_b64 s[14:15], s[52:53]
	s_add_u32 s14, s14, 1024
	s_addc_u32 s15, s15, 0
	s_mov_b32 s20, 6
	s_branch .Lwp_mat
.Lwp_ret_6:
	s_mov_b64 s[4:5], s[58:59]
	s_add_u32 s4, s4, 393216
	s_addc_u32 s5, s5, 0
	s_add_u32 s6, s50, 12386304
	s_addc_u32 s7, s51, 0
	s_mov_b32 s8, 3072
	s_mov_b32 s9, 256
	s_mov_b32 s10, 48
	s_mov_b32 s11, 192
	s_mov_b32 s12, 0x5555556
	s_mov_b32 s13, 0
	s_mov_b32 s16, 48
	s_mov_b64 s[14:15], s[56:57]
	s_add_u32 s14, s14, 512
	s_addc_u32 s15, s15, 0
	s_mov_b32 s20, 7
	s_branch .Lwp_mat

.Lwp_done:
	s_waitcnt vmcnt(0)
	s_mov_b64 s[0:1], s[84:85]
	s_mov_b32 s18, s86
	s_mov_b32 s19, s87
	s_mov_b64 s[22:23], s[88:89]
	s_mov_b64 s[26:27], s[92:93]
	s_mov_b64 s[30:31], s[94:95]
	v_mov_b32_e32 v0, v120
	v_mov_b32_e32 v1, v121
	v_mov_b32_e32 v57, v122

.LBB0_122:
	s_or_b64 exec, exec, s[0:1]
	s_andn2_b64 vcc, exec, s[10:11]
	s_cbranch_vccnz .LBB0_180
.LBB0_180:
	s_waitcnt vmcnt(0)
	s_barrier
	s_mov_b64 s[0:1], exec
	v_readlane_b32 s4, v253, 62
	v_readlane_b32 s5, v253, 63
	s_and_b64 s[4:5], s[0:1], s[4:5]
	s_mov_b64 exec, s[4:5]
	s_cbranch_execz .LBB0_232
	s_getreg_b32 s4, hwreg(HW_REG_XCC_ID, 0, 4)
	s_and_b32 s10, s4, 15
	s_cmp_lg_u32 0, -1
	s_cselect_b32 s4, 0, 0
	s_add_i32 s4, s4, 0x24000
	s_waitcnt vmcnt(9)
	v_mov_b32_e32 v0, s4
	s_waitcnt vmcnt(0) expcnt(0) lgkmcnt(0)
	ds_read_b32 v2, v0
	ds_read_b32 v0, v0 offset:4
	s_waitcnt lgkmcnt(1)
	v_cmp_ne_u32_e32 vcc, 0, v2
	s_cbranch_vccnz .LBB0_196
	s_mov_b32 s11, 1
	s_branch .LBB0_184
